# P7: leading half issues its conv-tap loads before its compensating barrier (loads only; scaling and halo write stay after it)
# baseline (speedup 1.0000x reference)
; #define PG8_LAS __attribute__((address_space(3)))
; #define PG8_BAR __builtin_amdgcn_s_barrier()
;     __device__ __forceinline__ void operator()(const f32x4 (&acc)[2][2][4][2], const Unit& u, int wr, int wc, int fr, int fq) const {
;         constexpr int FF = 2816, FF2 = 5632;
;         const int lcol = wc * 32 + 8 * fq, gcol = u.pn * HALF + lcol;
;         float rs[2][4];
;         load_rs(slots, u.pm * BM + wr * 64, fr, fq, 1.0f, rs);
;         if (fr >= 14) {
; #pragma unroll
;             for (int ai = 0; ai < 2; ++ai)
; #pragma unroll
;                 for (int bj = 0; bj < 2; ++bj)
; #pragma unroll
;                     for (int n = 0; n < 2; ++n) { const f32x4 x = acc[ai][bj][3][n] * rs[ai][3];
;                         *(PG8_LAS f32x4*)(halo + ((ai * 2 + wr) * 2 + (fr - 14)) * 256 + bj * HALF + lcol + 4 * n) = x;
;                         if (ai == 1 && wr == 1) *(f32x4*)(rawh + (size_t)(u.pm * 2 + (fr - 14)) * FF2 + bj * FF + gcol + 4 * n) = x; }
;         }
;         f32x4 w0[2], w1[2], w2[2], bb[2];
; #pragma unroll
;         for (int bj = 0; bj < 2; ++bj) { const int col = bj * FF + gcol;
;             w0[bj] = *(const f32x4*)(cw + col); w1[bj] = *(const f32x4*)(cw + FF2 + col); w2[bj] = *(const f32x4*)(cw + 2 * FF2 + col); bb[bj] = *(const f32x4*)(cb + col); }
; template <class Epi, class Sched, bool ALIGN_EPI = false, bool SP2 = false>
; __device__ __forceinline__ void gemm_phase(PG8_LAS unsigned char* lds, const Gemm g, const Sched& S, const Epi& E, int wave_in) {
;     ...
;         if constexpr (ALIGN_EPI) { if (wr == 0) PG8_BAR; }
.Lkexit_6:
.LBB0_900:
	v_readlane_b32 s18, v255, 37
	v_readlane_b32 s19, v255, 38
	s_lshl_b32 s5, s71, 8
	s_add_i32 s5, s5, s8
	s_lshl_b32 s11, s71, 1
	s_movk_i32 s29, 0x1600
	s_mov_b32 s100, 0xbfb8aa3b
	s_mov_b32 s79, 0
	v_cmp_eq_u32_e64 s[98:99], 15, v206
	v_lshl_or_b32 v233, s69, 7, v208
	v_lshlrev_b32_e32 v237, 2, v206
	v_lshlrev_b32_e32 v233, 2, v233
	v_or_b32_e32 v239, s5, v206
	v_add_u32_e32 v235, 0x2c00, v233
	global_load_dwordx4 v[128:131], v233, s[14:15]
	global_load_dwordx4 v[132:135], v233, s[16:17]
	global_load_dwordx4 v[136:139], v233, s[92:93]
	global_load_dwordx4 v[140:143], v233, s[60:61]
	global_load_dwordx4 v[144:147], v235, s[14:15]
	global_load_dwordx4 v[148:151], v235, s[16:17]
	global_load_dwordx4 v[152:155], v235, s[92:93]
	global_load_dwordx4 v[156:159], v235, s[60:61]
	v_lshrrev_b32_e32 v243, 1, v233
	v_add_u32_e32 v241, s11, v206
	v_mad_u32_u24 v239, v239, s29, v243
	v_mad_u32_u24 v241, v241, s70, v233
	s_and_b64 vcc, exec, s[94:95]
	s_cbranch_vccz .Lp7_nocomp
	s_barrier
.Lp7_nocomp:
	s_cmp_eq_u32 s101, s71
	v_add_u32_e32 v249, 0x2c00, v241
	s_cbranch_scc1 .Lp7_rsok
	v_or_b32_e32 v229, s5, v209
	v_lshlrev_b32_e32 v229, 6, v229
	v_add_u32_e32 v231, 0x2000, v229
	global_load_dwordx4 v[160:163], v229, s[26:27]
	global_load_dwordx4 v[164:167], v229, s[26:27] offset:16
	global_load_dwordx4 v[178:181], v229, s[26:27] offset:32
	global_load_dwordx4 v[182:185], v229, s[26:27] offset:48
	global_load_dwordx4 v[186:189], v231, s[26:27]
	global_load_dwordx4 v[194:197], v231, s[26:27] offset:16
	global_load_dwordx4 v[198:201], v231, s[26:27] offset:32
	global_load_dwordx4 v[202:205], v231, s[26:27] offset:48
	s_waitcnt vmcnt(0)
	v_pk_add_f32 v[162:163], v[162:163], v[166:167]
	v_pk_add_f32 v[188:189], v[188:189], v[196:197]
	v_pk_add_f32 v[160:161], v[160:161], v[164:165]
	v_pk_add_f32 v[186:187], v[186:187], v[194:195]
	v_pk_add_f32 v[164:165], v[180:181], v[184:185]
	v_pk_add_f32 v[194:195], v[200:201], v[204:205]
	v_pk_add_f32 v[166:167], v[178:179], v[182:183]
	v_pk_add_f32 v[196:197], v[198:199], v[202:203]
	v_pk_add_f32 v[162:163], v[162:163], v[164:165]
	v_pk_add_f32 v[188:189], v[188:189], v[194:195]
	v_pk_add_f32 v[160:161], v[160:161], v[166:167]
	v_pk_add_f32 v[186:187], v[186:187], v[196:197]
	v_add_f32_e32 v160, v160, v161
	v_add_f32_e32 v186, v186, v187
	v_add_f32_e32 v161, v162, v163
	v_add_f32_e32 v187, v188, v189
	v_add_f32_e32 v160, v160, v161
	v_add_f32_e32 v186, v186, v187
	v_fmamk_f32 v160, v160, 0x3a800000, v244
	v_fmamk_f32 v186, v186, 0x3a800000, v244
	v_rsq_f32_e32 v160, v160
	v_rsq_f32_e32 v186, v186
	ds_bpermute_b32 v228, v237, v160
	ds_bpermute_b32 v230, v237, v160 offset:64
	ds_bpermute_b32 v232, v237, v160 offset:128
	ds_bpermute_b32 v234, v237, v160 offset:192
	ds_bpermute_b32 v236, v237, v186
	ds_bpermute_b32 v238, v237, v186 offset:64
	ds_bpermute_b32 v240, v237, v186 offset:128
	ds_bpermute_b32 v248, v237, v186 offset:192
	s_mov_b32 s101, s71
